# attention loop: one static s_setprio 1 for waves 4-7 before the loop (reset to 0 at exit)
# baseline (speedup 1.0000x reference)
; #define ATT_STAGE_LOAD(SRC, IT) do { _Pragma("unroll") for (int i_ = 0; i_ < 12; ++i_) { const int chunk_ = tid + 512 * i_, rr_ = chunk_ >> 4, ch_ = chunk_ & 15, lv_ = (IT).lq0 - 128 + rr_; \
;         u32x4 val_ = {0u, 0u, 0u, 0u}; if (lv_ >= 0) val_ = *(const u32x4*)((SRC) + ((size_t)lv_ * (IT).d + (IT).res) * 1024 + (IT).hh * 128 + ch_ * 8); stg[i_] = val_; } } while (0)
; #define ATT_QLOAD(IT) do { const size_t qp_ = (size_t)((IT).lq0 + 32 * wave + r) * (IT).d + (IT).res; const bf16* q_ = Q + qp_ * 1024 + (IT).hh * 128 + 8 * h; \
;         _Pragma("unroll") for (int s_ = 0; s_ < 8; ++s_) qf[s_] = *(const bf16x8*)(q_ + 16 * s_); } while (0)
; __device__ __forceinline__ void attn_phase(LAS unsigned char* lds, const bf16* __restrict__ Q, const bf16* __restrict__ Kb, const bf16* __restrict__ Vb, unsigned char* ws, float* PM, int tid, int wave, int lane) {
;     ...
;     AttnItem I = attn_decode(it);
;     u32x4 stg[12]; bf16x8 qf[8];
;     ...
;     ATT_STAGE_LOAD(Kb, I); ATT_QLOAD(I);
.LBB0_572:
	s_or_b64 exec, exec, s[0:1]
	v_add_u32_e32 v1, 0xa00, v186
	v_or_b32_e32 v202, 0x80, v198
	v_lshrrev_b32_e32 v203, 4, v1
	v_add_u32_e32 v4, s3, v202
	v_mov_b32_e32 v5, v80
	v_add_u32_e32 v6, s3, v203
	v_mov_b32_e32 v7, v80
	v_lshlrev_b64 v[4:5], s2, v[4:5]
	v_lshlrev_b64 v[6:7], s2, v[6:7]
	v_lshl_add_u64 v[4:5], v[4:5], 0, s[70:71]
	v_lshl_add_u64 v[6:7], v[6:7], 0, s[70:71]
	v_lshlrev_b64 v[4:5], 11, v[4:5]
	v_lshlrev_b64 v[6:7], 11, v[6:7]
	v_add_u32_e32 v1, 0xe00, v186
	v_lshl_add_u64 v[4:5], v[2:3], 0, v[4:5]
	v_lshl_add_u64 v[6:7], v[2:3], 0, v[6:7]
	v_or_b32_e32 v204, 0xc0, v198
	v_lshrrev_b32_e32 v205, 4, v1
	global_load_dwordx4 v[100:103], v[4:5], off
	global_load_dwordx4 v[104:107], v[6:7], off
	v_add_u32_e32 v4, s3, v204
	v_mov_b32_e32 v5, v80
	v_add_u32_e32 v6, s3, v205
	v_mov_b32_e32 v7, v80
	v_lshlrev_b64 v[4:5], s2, v[4:5]
	v_lshlrev_b64 v[6:7], s2, v[6:7]
	v_lshl_add_u64 v[4:5], v[4:5], 0, s[70:71]
	v_lshl_add_u64 v[6:7], v[6:7], 0, s[70:71]
	v_lshlrev_b64 v[4:5], 11, v[4:5]
	v_lshlrev_b64 v[6:7], 11, v[6:7]
	v_add_u32_e32 v1, 0x1200, v186
	v_lshl_add_u64 v[4:5], v[2:3], 0, v[4:5]
	v_lshl_add_u64 v[6:7], v[2:3], 0, v[6:7]
	v_or_b32_e32 v206, 0x100, v198
	v_lshrrev_b32_e32 v207, 4, v1
	global_load_dwordx4 v[112:115], v[4:5], off
	global_load_dwordx4 v[128:131], v[6:7], off
	v_add_u32_e32 v4, s3, v206
	v_mov_b32_e32 v5, v80
	v_add_u32_e32 v6, s3, v207
	v_mov_b32_e32 v7, v80
	v_lshlrev_b64 v[4:5], s2, v[4:5]
	v_lshlrev_b64 v[6:7], s2, v[6:7]
	v_lshl_add_u64 v[4:5], v[4:5], 0, s[70:71]
	v_lshl_add_u64 v[6:7], v[6:7], 0, s[70:71]
	v_lshlrev_b64 v[4:5], 11, v[4:5]
	v_lshlrev_b64 v[6:7], 11, v[6:7]
	v_add_u32_e32 v1, 0x1600, v186
	v_lshl_add_u64 v[4:5], v[2:3], 0, v[4:5]
	v_lshl_add_u64 v[6:7], v[2:3], 0, v[6:7]
	v_or_b32_e32 v208, 0x140, v198
	v_lshrrev_b32_e32 v209, 4, v1
	global_load_dwordx4 v[148:151], v[4:5], off
	global_load_dwordx4 v[152:155], v[6:7], off
	v_add_u32_e32 v4, s3, v208
	v_mov_b32_e32 v5, v80
	v_add_u32_e32 v6, s3, v209
	v_mov_b32_e32 v7, v80
	v_lshlrev_b64 v[4:5], s2, v[4:5]
	v_lshlrev_b64 v[6:7], s2, v[6:7]
	v_lshl_add_u64 v[4:5], v[4:5], 0, s[70:71]
	v_lshl_add_u64 v[6:7], v[6:7], 0, s[70:71]
	v_lshlrev_b64 v[4:5], 11, v[4:5]
	v_lshlrev_b64 v[6:7], 11, v[6:7]
	s_lshl_b32 s33, s10, 5
	v_lshl_add_u64 v[4:5], v[2:3], 0, v[4:5]
	v_lshl_add_u64 v[2:3], v[2:3], 0, v[6:7]
	s_add_i32 s1, s33, s85
	global_load_dwordx4 v[156:159], v[4:5], off
	global_load_dwordx4 v[160:163], v[2:3], off
	v_or_b32_e32 v2, s1, v185
	v_mov_b32_e32 v3, v80
	v_lshlrev_b64 v[2:3], s2, v[2:3]
	v_lshl_add_u64 v[2:3], v[2:3], 0, s[70:71]
	v_lshlrev_b64 v[2:3], 11, v[2:3]
	v_lshl_add_u64 v[2:3], s[14:15], 0, v[2:3]
	s_lshl_b32 s96, s6, 1
	v_lshl_add_u64 v[2:3], v[2:3], 0, s[96:97]
	v_lshlrev_b32_e32 v6, 4, v187
	v_mov_b32_e32 v7, v80
	v_lshl_add_u64 v[2:3], v[2:3], 0, v[6:7]
	global_load_dwordx4 v[108:111], v[2:3], off
	global_load_dwordx4 v[116:119], v[2:3], off offset:32
	global_load_dwordx4 v[120:123], v[2:3], off offset:64
	global_load_dwordx4 v[124:127], v[2:3], off offset:96
	global_load_dwordx4 v[132:135], v[2:3], off offset:128
	global_load_dwordx4 v[136:139], v[2:3], off offset:160
	global_load_dwordx4 v[140:143], v[2:3], off offset:192
	global_load_dwordx4 v[144:147], v[2:3], off offset:224
	v_lshlrev_b32_e32 v1, 4, v186
	v_and_b32_e32 v1, 0xf0, v1
	v_add_u32_e32 v2, 0, v1
	v_mov_b32_e32 v1, v80
	v_lshl_add_u64 v[190:191], s[4:5], 0, v[0:1]
	v_cmp_gt_u32_e64 s[4:5], 32, v184
	v_lshlrev_b32_e32 v5, 2, v187
	v_or_b32_e32 v14, 1, v5
	v_writelane_b32 v245, s4, 46
	v_lshl_add_u64 v[188:189], s[12:13], 0, v[0:1]
	v_bfe_u32 v0, v186, 2, 2
	v_writelane_b32 v245, s5, 47
	v_cmp_gt_u32_e64 s[4:5], v5, v185
	v_and_b32_e32 v1, 16, v186
	v_lshlrev_b32_e32 v7, 2, v186
; #define LAS __attribute__((address_space(3)))
; __device__ __forceinline__ void attn_phase(LAS unsigned char* lds, const bf16* __restrict__ Q, const bf16* __restrict__ Kb, const bf16* __restrict__ Vb, unsigned char* ws, float* PM, int tid, int wave, int lane) {
;     ...
;         const LAS unsigned char* kb = lds + (32 * wave + r) * KROW + h * 16;
;         const int lkw = I.lq0 - 128 + 32 * wave;
; #pragma unroll
;         for (int i = 0; i < 5; ++i) {
; #pragma unroll
;             for (int e = 0; e < 16; ++e) sacc[i][e] = 0.f;
; #pragma unroll
;             for (int s = 0; s < 8; ++s) { const bf16x8 kf = *(const LAS bf16x8*)(kb + (32 * i) * KROW + 32 * s); sacc[i] = __builtin_amdgcn_mfma_f32_32x32x16_bf16(kf, qf[s], sacc[i], 0, 0, 0); }
;         }
; #pragma unroll
;         for (int e = 0; e < 16; ++e) { const int kv = (e & 3) + 8 * (e >> 2) + 4 * h; if (kv < r) sacc[0][e] = -INFINITY; if (kv > r) sacc[4][e] = -INFINITY; }
;     ...
;         const LAS unsigned char* vbase = lds + (32 * wave + 4 * h + ((lane & 15) >> 2)) * VROW + (16 * ((lane >> 4) & 1) + 4 * (lane & 3)) * 2;
	v_writelane_b32 v245, s4, 48
	s_movk_i32 s0, 0x140
	v_or3_b32 v0, v0, v5, s33
	v_writelane_b32 v245, s5, 49
	v_cmp_lt_u32_e64 s[4:5], v14, v185
	v_or_b32_e32 v14, 2, v5
	v_cmp_lt_u32_e64 s[12:13], v14, v185
	v_cmp_gt_u32_e64 s[14:15], v14, v185
	v_or_b32_e32 v14, 3, v5
	v_cmp_lt_u32_e64 s[16:17], v14, v185
	v_cmp_gt_u32_e64 s[24:25], v14, v185
	v_or_b32_e32 v14, 8, v5
	v_cmp_lt_u32_e64 s[26:27], v14, v185
	v_cmp_gt_u32_e64 s[72:73], v14, v185
	v_or_b32_e32 v14, 9, v5
	v_cmp_lt_u32_e64 s[74:75], v14, v185
	v_cmp_gt_u32_e64 s[78:79], v14, v185
	v_or_b32_e32 v14, 10, v5
	v_cmp_lt_u32_e64 s[28:29], v14, v185
	v_cmp_gt_u32_e64 s[30:31], v14, v185
	v_or_b32_e32 v14, 11, v5
	v_cmp_lt_u32_e64 s[34:35], v14, v185
	v_cmp_gt_u32_e64 s[36:37], v14, v185
	v_or_b32_e32 v14, 16, v5
	v_cmp_lt_u32_e64 s[38:39], v14, v185
	v_cmp_gt_u32_e64 s[40:41], v14, v185
	v_or_b32_e32 v14, 17, v5
	v_cmp_lt_u32_e64 s[42:43], v14, v185
	v_cmp_gt_u32_e64 s[44:45], v14, v185
	v_or_b32_e32 v14, 18, v5
	v_cmp_lt_u32_e64 s[46:47], v14, v185
	v_cmp_gt_u32_e64 s[48:49], v14, v185
	v_or_b32_e32 v14, 19, v5
	v_and_or_b32 v1, v7, 12, v1
	v_cmp_lt_u32_e64 s[50:51], v14, v185
	v_cmp_gt_u32_e64 s[52:53], v14, v185
	v_or_b32_e32 v14, 24, v5
	v_or_b32_e32 v210, s33, v185
	s_movk_i32 s1, 0x110
	v_mul_lo_u32 v0, v0, s0
	v_lshlrev_b32_e32 v1, 1, v1
	v_writelane_b32 v245, s4, 50
	v_cmp_lt_u32_e64 s[54:55], v14, v185
	v_cmp_gt_u32_e64 s[56:57], v14, v185
	v_or_b32_e32 v14, 25, v5
	v_mul_lo_u32 v3, v210, s1
	v_add3_u32 v211, 0, v0, v1
	v_lshrrev_b32_e32 v0, 1, v186
	v_mov_b32_e32 v7, 0x4400
	v_mov_b32_e32 v9, 0x8800
	v_cmp_lt_u32_e64 s[6:7], v5, v185
	v_writelane_b32 v245, s5, 51
	v_cmp_lt_u32_e64 s[58:59], v14, v185
	v_cmp_gt_u32_e64 s[60:61], v14, v185
	v_or_b32_e32 v14, 26, v5
	v_or_b32_e32 v5, 27, v5
	v_mov_b32_e32 v15, 0x5000
	v_mov_b32_e32 v17, 0xa000
	v_lshlrev_b32_e32 v4, 3, v187
	v_add_u32_e32 v3, 0, v3
	v_and_b32_e32 v192, 16, v0
	v_mul_u32_u24_e32 v0, 0x110, v198
	v_mul_u32_u24_e32 v1, 0x110, v199
	v_mad_u32_u24 v7, v198, s1, v7
	v_mul_u32_u24_e32 v8, 0x110, v201
	v_mad_u32_u24 v9, v198, s1, v9
	v_mul_u32_u24_e32 v10, 0x110, v203
	v_mul_u32_u24_e32 v11, 0x110, v205
	v_mul_u32_u24_e32 v12, 0x110, v207
	v_mul_u32_u24_e32 v13, 0x110, v209
	v_cmp_lt_u32_e64 s[62:63], v14, v185
	v_cmp_gt_u32_e64 s[64:65], v14, v185
	v_cmp_lt_u32_e64 s[66:67], v5, v185
	v_cmp_gt_u32_e64 s[68:69], v5, v185
	v_mul_u32_u24_e32 v5, 0x140, v198
	v_mul_u32_u24_e32 v14, 0x140, v199
	v_mad_u32_u24 v15, v198, s0, v15
	v_mul_u32_u24_e32 v16, 0x140, v201
	v_mad_u32_u24 v17, v198, s0, v17
	v_mul_u32_u24_e32 v18, 0x140, v203
	v_mul_u32_u24_e32 v19, 0x140, v205
	v_mul_u32_u24_e32 v20, 0x140, v207
	v_mul_u32_u24_e32 v21, 0x140, v209
	v_readlane_b32 s0, v245, 44
	s_lshl_b32 s3, 1, s2
	v_mov_b32_e32 v193, v80
	v_add_u32_e32 v212, v2, v0
	v_add_u32_e32 v213, v2, v1
	v_add_u32_e32 v214, v2, v8
	v_add_u32_e32 v215, v2, v10
	v_add_u32_e32 v216, v2, v11
	v_add_u32_e32 v217, v2, v7
	v_add_u32_e32 v218, v2, v12
	v_add_u32_e32 v219, v2, v9
	v_add_u32_e32 v220, v2, v13
	v_add_u32_e32 v221, v3, v6
	v_add_u32_e32 v222, v2, v5
	v_add_u32_e32 v223, v2, v14
	v_add_u32_e32 v224, v2, v16
	v_add_u32_e32 v225, v2, v18
	v_add_u32_e32 v226, v2, v19
	v_add_u32_e32 v227, v2, v15
	v_add_u32_e32 v228, v2, v20
	v_add_u32_e32 v229, v2, v17
	v_add_u32_e32 v230, v2, v21
	v_lshlrev_b32_e32 v194, 1, v4
	v_mov_b32_e32 v231, 0xff800000
	s_mov_b32 s96, s70
	s_mov_b32 s2, s0
	v_readlane_b32 s1, v245, 45
	s_cmp_lt_u32 s11, 4
	s_cbranch_scc1 .Latt_prio_done
	s_setprio 1
.Latt_prio_done:
	s_branch .LBB0_574
.LBB0_573:
	s_or_b64 exec, exec, s[0:1]
	s_andn2_b64 vcc, exec, s[70:71]
	s_mov_b32 s84, s92
	s_mov_b32 s93, s5
	s_mov_b32 s3, s95
	s_mov_b32 s96, s94
	s_mov_b32 s85, s4
	s_cbranch_vccz .LBB0_596

; #define LAS __attribute__((address_space(3)))
; #define LBAR() do { asm volatile("s_waitcnt lgkmcnt(0)" ::: "memory"); __builtin_amdgcn_s_barrier(); asm volatile("" ::: "memory"); } while (0)
; __device__ __forceinline__ void s5_state_block(LAS unsigned char* lds, const bf16* __restrict__ WST, const bf16* __restrict__ U, float* SC, int vb, int tid, int wave, int lane) {
;     constexpr int WROW = 1040;
;     const int g = vb >> 2;
;     LBAR();
;     { const u32x4* src = (const u32x4*)(WST + (size_t)g * 128 * 512);
;       u32x4 tmp[16];
; #pragma unroll
;       for (int i = 0; i < 16; ++i) tmp[i] = src[tid + 512 * i];
; #pragma unroll
;       for (int i = 0; i < 16; ++i) { const int chunk = tid + 512 * i, row = chunk >> 6, ch = chunk & 63; *(LAS u32x4*)(lds + row * WROW + ch * 16) = tmp[i]; } }
;     LBAR();
;     const int half = wave & 1, ct = 4 * (vb & 3) + (wave >> 1), r = lane & 31, h = lane >> 5, c = ct * 32 + r;
;     f32x16 acc[2];
; #pragma unroll
;     for (int i = 0; i < 2; ++i)
; #pragma unroll
;         for (int e = 0; e < 16; ++e) acc[i][e] = 0.f;
;     const bf16* ub = U + ((size_t)g * S + (size_t)c * 32) * 16 + 8 * h;
;     const LAS unsigned char* wl = lds + (64 * half + r) * WROW + h * 16;
; __global__ void __launch_bounds__(512, 2) mega(Args a) {
;     ...
;         for (int vb = blockIdx.x; vb < 256; vb += gridDim.x) s5_state_block(lds, WST, Ub, SC, vb, tid, wave, lane);
.LBB0_596:
	s_setprio 0
	v_readlane_b32 s66, v245, 44
	v_readlane_b32 s68, v245, 42
	s_cmpk_gt_i32 s66, 0xff
	s_mov_b32 s65, s11
	v_readlane_b32 s69, v245, 43
	v_readlane_b32 s67, v245, 45
	s_cbranch_scc1 .LBB0_599
	v_or_b32_e32 v0, 0x400, v186
	v_lshrrev_b32_e32 v16, 6, v186
	v_or_b32_e32 v2, 0x800, v186
	v_mul_u32_u24_e32 v17, 0x410, v16
	v_lshrrev_b32_e32 v16, 6, v0
	v_or_b32_e32 v4, 0xc00, v186
	v_mul_u32_u24_e32 v18, 0x410, v16
	v_lshrrev_b32_e32 v16, 6, v2
	v_or_b32_e32 v6, 0x1000, v186
	v_mul_u32_u24_e32 v19, 0x410, v16
	v_lshrrev_b32_e32 v16, 6, v4
	v_or_b32_e32 v8, 0x1400, v186
	v_mul_u32_u24_e32 v20, 0x410, v16
	v_lshrrev_b32_e32 v16, 6, v6
	v_or_b32_e32 v10, 0x1800, v186
	v_mul_u32_u24_e32 v21, 0x410, v16
	v_lshrrev_b32_e32 v16, 6, v8
	v_or_b32_e32 v12, 0x1c00, v186
	v_mul_u32_u24_e32 v22, 0x410, v16
	v_lshrrev_b32_e32 v16, 6, v10
	v_readlane_b32 s0, v245, 1
	v_mul_u32_u24_e32 v23, 0x410, v16
	v_lshrrev_b32_e32 v16, 6, v12
	s_lshr_b32 s2, s0, 7
	s_and_b32 s0, s0, 64
	v_add_u32_e32 v1, 0x200, v186
	v_add_u32_e32 v3, 0x600, v186
	v_add_u32_e32 v5, 0xa00, v186
	v_add_u32_e32 v7, 0xe00, v186
	v_add_u32_e32 v9, 0x1200, v186
	v_add_u32_e32 v11, 0x1600, v186
	v_add_u32_e32 v13, 0x1a00, v186
	v_add_u32_e32 v14, 0x1e00, v186
	v_lshlrev_b32_e32 v15, 4, v186
	v_mul_u32_u24_e32 v24, 0x410, v16
	v_or_b32_e32 v16, s0, v185
	v_and_b32_e32 v15, 0x3f0, v15
	v_lshrrev_b32_e32 v1, 6, v1
	v_lshrrev_b32_e32 v3, 6, v3
	v_lshrrev_b32_e32 v5, 6, v5
	v_lshrrev_b32_e32 v7, 6, v7
	v_lshrrev_b32_e32 v9, 6, v9
	v_lshrrev_b32_e32 v11, 6, v11
	v_lshrrev_b32_e32 v13, 6, v13
	v_lshrrev_b32_e32 v14, 6, v14
	v_mul_u32_u24_e32 v16, 0x410, v16
	v_lshlrev_b32_e32 v26, 4, v187
	v_mov_b32_e32 v33, 0
	v_add_u32_e32 v15, 0, v15
	v_mul_u32_u24_e32 v1, 0x410, v1
	v_mul_u32_u24_e32 v3, 0x410, v3
	v_mul_u32_u24_e32 v5, 0x410, v5
	v_mul_u32_u24_e32 v7, 0x410, v7
	v_mul_u32_u24_e32 v9, 0x410, v9
	v_mul_u32_u24_e32 v11, 0x410, v11
	v_mul_u32_u24_e32 v13, 0x410, v13
	v_mul_u32_u24_e32 v25, 0x410, v14
	v_lshlrev_b32_e32 v14, 3, v187
	v_add3_u32 v42, 0, v16, v26
	v_lshlrev_b32_e32 v16, 2, v187
	v_readlane_b32 s28, v245, 7
	v_readlane_b32 s30, v245, 34
	v_readlane_b32 s34, v245, 36
	s_mov_b32 s1, 0
	s_lshl_b32 s3, s66, 2
	s_lshl_b32 s8, s28, 2
	v_lshlrev_b32_e32 v34, 4, v186
	v_mov_b32_e32 v35, v33
	s_movk_i32 s9, 0x2000
	v_lshlrev_b32_e32 v43, 4, v0
	s_movk_i32 s10, 0x6000
	v_lshlrev_b32_e32 v44, 4, v2
	s_mov_b32 s11, 0xa000
	v_lshlrev_b32_e32 v45, 4, v4
	s_mov_b32 s12, 0xe000
	v_lshlrev_b32_e32 v46, 4, v6
	s_mov_b32 s13, 0x12000
	v_lshlrev_b32_e32 v47, 4, v8
	s_mov_b32 s14, 0x16000
	v_lshlrev_b32_e32 v48, 4, v10
	s_mov_b32 s15, 0x1a000
	v_lshlrev_b32_e32 v49, 4, v12
	s_mov_b32 s16, 0x1e000
	v_add_u32_e32 v50, v15, v17
	v_add_u32_e32 v51, v15, v1
	v_add_u32_e32 v52, v15, v18
	v_add_u32_e32 v53, v15, v3
	v_add_u32_e32 v54, v15, v19
	v_add_u32_e32 v55, v15, v5
	v_add_u32_e32 v56, v15, v20
	v_add_u32_e32 v57, v15, v7
	v_add_u32_e32 v58, v15, v21
	v_add_u32_e32 v59, v15, v9
	v_add_u32_e32 v60, v15, v22
	v_add_u32_e32 v61, v15, v11
	v_add_u32_e32 v62, v15, v23
	v_add_u32_e32 v63, v15, v13
	v_add_u32_e32 v64, v15, v24
	v_add_u32_e32 v65, v15, v25
	v_lshlrev_b32_e32 v36, 1, v14
	v_mov_b32_e32 v37, v33
	s_lshl_b32 s0, s0, 2
	v_lshlrev_b32_e32 v38, 2, v16
	v_mov_b32_e32 v39, v33
	s_mov_b32 s17, s66
	v_readlane_b32 s31, v245, 35
	v_readlane_b32 s35, v245, 37
	v_readlane_b32 s29, v245, 8
